# attention: one SGPR base advance per two tiles, per-lane tile-row offsets precomputed (on top of static prio)
# baseline (speedup 1.0000x reference)
; __device__ __forceinline__ int lane_id_asm() { int l; asm volatile("v_mbcnt_lo_u32_b32 %0, -1, 0\n\tv_mbcnt_hi_u32_b32 %0, -1, %0" : "=v"(l)); return l; }
; __device__ __forceinline__ int v_st(int k, int c) { const int kk = (k & ~0xC) | ((k & 4) << 1) | ((k & 8) >> 1); return ((kk >> 3) * 4 + (c >> 5)) * 512 + ((kk & 7) * 32 + (c & 31)) * 2; }
; __device__ __forceinline__ int v_rd_base(int lane) { return ((lane & 3) << 3) | (((lane >> 2) & 3) << 6) | (((lane >> 4) & 1) << 5) | (((lane >> 5) & 1) << 8); }
; #define SLOAD(i, k0) do { sr_[i].vs0 = St::ld8(&Vh[(long)((k0) + sr) * LDK + sc]); sr_[i].vs1 = St::ld8(&Vh[(long)((k0) + 32 + sr) * LDK + sc]); \
;     sr_[i].ks0 = St::ld8(&Kh[(long)((k0) + sr) * LDK + sc]); sr_[i].ks1 = St::ld8(&Kh[(long)((k0) + 32 + sr) * LDK + sc]); } while (0)
; template <typename TQ>
; __device__ __forceinline__ void attn_dense_body(const TQ* __restrict__ Qb, const bf16* __restrict__ Kh, const bf16* __restrict__ Vh,
;                                                 unsigned short* __restrict__ Ob, int seq, char* lds, const int wave_s) {
;     ...
;   const int lane = lane_id_asm(), wid = wave_s, tid = wave_s * 64 + lane, r32 = lane & 31, hi = lane >> 5;
;   bf16* V_lds = (bf16*)lds; bf16* K_lds = (bf16*)(lds + 2 * SHM_V);
;   float* ws = (float*)(lds + 2 * SHM_V + 2 * SHM_K) + wid * 64; float* li_l = ws; float* al_l = ws + 32;
;   float m_reg = -1e30f, l_reg = 0; f32x16 o[4] = {}; bf16x8 qr[8];
;   const TQ* Qw = Qb + (long)(wid * QBLK + r32) * LDQ + hi * 8;
; #pragma unroll
;   for (int d0 = 0; d0 < 8; ++d0) qr[d0] = SQ::tobf(SQ::ld8(Qw + d0 * 16));
;   const int sr = tid >> 4, sc = (tid & 15) * 8, vst0 = v_st(sr, sc), vst1 = v_st(32 + sr, sc);
;   const int vb0 = (int)(uintptr_t)V_lds + v_rd_base(lane);
;   struct { typename St::T vs0, vs1, ks0, ks1; } sr_[SDEPTH];
;     ...
;   f32x16 pA0, pA1, pB0, pB1; float mnA, mnB, alA, alB; bf16x8 pa0, pa1, pa2, pa3; const int NT = seq / KVBLK;
;   constexpr int SE = 0, SO = SDEPTH - 1;
;   SLOAD(SE, 0); asm volatile("s_waitcnt vmcnt(0)" ::: "memory"); SWRITE(0, SE); __syncthreads();
;   qkt(pA0, pA1, K_lds, qr, r32, hi); partialSM(pA0, pA1, m_reg, mnA, alA);
.LBB0_574:
	s_mul_i32 s39, s2, 0xc00
	s_mul_hi_u32 s38, s2, 0xc00
	s_add_u32 s45, s6, s39
	s_addc_u32 s47, s7, s38
	s_lshl_b32 s38, s42, 7
	s_ashr_i32 s39, s38, 31
	s_lshl_b64 s[42:43], s[38:39], 1
	s_add_u32 s46, s45, s42
	s_addc_u32 s47, s47, s43
	s_lshl_b64 s[38:39], s[40:41], 1
	s_add_u32 s50, s6, s38
	s_addc_u32 s51, s7, s39
	s_lshl_b32 s44, s44, 7
	s_ashr_i32 s45, s44, 31
	s_lshl_b64 s[38:39], s[44:45], 1
	s_add_u32 s38, s50, s38
	v_readlane_b32 s50, v255, 42
	v_mbcnt_lo_u32_b32 v68, -1, 0
	v_mbcnt_hi_u32_b32 v68, -1, v68
	s_addc_u32 s39, s51, s39
	v_lshlrev_b32_e32 v64, 3, v68
	v_add_u32_e32 v20, s50, v68
	v_ashrrev_i32_e32 v69, 4, v20
	v_add_u32_e32 v21, 32, v69
	v_and_b32_e32 v70, 0x78, v64
	v_mad_i64_i32 v[0:1], s[50:51], v69, s97, 0
	v_mad_i64_i32 v[4:5], s[50:51], v21, s97, 0
	v_or_b32_e32 v0, v0, v70
	v_or_b32_e32 v4, v4, v70
	v_lshl_add_u64 v[8:9], v[0:1], 1, s[38:39]
	v_lshl_add_u64 v[12:13], v[4:5], 1, s[38:39]
	global_load_dwordx4 v[0:3], v[8:9], off offset:2560
	global_load_dwordx4 v[4:7], v[12:13], off offset:2560
	s_nop 0
	global_load_dwordx4 v[8:11], v[8:9], off offset:2048
	s_nop 0
	global_load_dwordx4 v[12:15], v[12:13], off offset:2048
	v_and_b32_e32 v178, 31, v68
	v_readlane_b32 s50, v255, 43
	v_ashrrev_i32_e32 v179, 5, v68
	v_mov_b64_e32 v[16:17], s[46:47]
	v_or_b32_e32 v18, s50, v178
	v_mad_i64_i32 v[16:17], s[46:47], v18, s33, v[16:17]
	v_lshlrev_b32_e32 v18, 3, v179
	v_ashrrev_i32_e32 v19, 31, v18
	v_lshl_add_u64 v[16:17], v[18:19], 1, v[16:17]
	global_load_dwordx4 v[112:115], v[16:17], off
	global_load_dwordx4 v[108:111], v[16:17], off offset:32
	global_load_dwordx4 v[120:123], v[16:17], off offset:64
	global_load_dwordx4 v[124:127], v[16:17], off offset:96
	global_load_dwordx4 v[116:119], v[16:17], off offset:128
	global_load_dwordx4 v[104:107], v[16:17], off offset:160
	global_load_dwordx4 v[100:103], v[16:17], off offset:192
	global_load_dwordx4 v[96:99], v[16:17], off offset:224
	v_and_b32_e32 v19, 0x70, v20
	v_and_b32_e32 v20, 0xfffff0, v69
	v_lshlrev_b32_e32 v22, 1, v69
	v_lshrrev_b32_e32 v23, 1, v69
	v_and_b32_e32 v24, 3, v69
	v_and_or_b32 v20, v69, 8, v20
	v_and_or_b32 v22, v69, 4, v24
	v_and_b32_e32 v24, 0xfffff0, v21
	v_lshlrev_b32_e32 v28, 1, v21
	v_bfe_u32 v18, v64, 5, 2
	v_lshlrev_b32_e32 v25, 1, v70
	v_lshlrev_b32_e32 v26, 8, v69
	v_lshlrev_b32_e32 v21, 8, v21
	v_lshrrev_b32_e32 v20, 1, v20
	v_and_or_b32 v24, v69, 8, v24
	v_lshlrev_b32_e32 v48, 4, v68
	v_bitop3_b32 v26, v25, v26, v19 bitop3:0xde
	v_bitop3_b32 v19, v21, v25, v19 bitop3:0xf6
	v_or_b32_e32 v20, v20, v18
	v_lshrrev_b32_e32 v21, 1, v24
	v_lshlrev_b32_e32 v180, 4, v179
	v_lshlrev_b32_e32 v65, 8, v178
	v_and_b32_e32 v66, 0x70, v48
	v_and_b32_e32 v23, 48, v25
	v_lshlrev_b32_e32 v22, 6, v22
	v_add_u32_e32 v186, 0x8000, v19
	v_lshlrev_b32_e32 v19, 9, v20
	v_or_b32_e32 v18, v21, v18
	v_xad_u32 v27, v66, v180, v65
	v_or3_b32 v19, v19, v22, v23
	v_lshlrev_b32_e32 v18, 9, v18
	v_or3_b32 v18, v18, v22, v23
	v_add_u32_e32 v187, 0, v19
	v_add_u32_e32 v189, 0x8000, v27
	v_add_u32_e32 v185, 0x8000, v26
	v_add_u32_e32 v188, 0, v18
	s_waitcnt vmcnt(0)
	v_readlane_b32 s51, v255, 44
	s_cmp_lg_u32 0, -1
	s_cselect_b32 s51, 0, 0
	s_mov_b32 s81, s80
	s_mov_b32 s82, s80
	s_mov_b32 s83, s80
	s_mov_b32 s84, s80
	s_mov_b32 s85, s80
	s_mov_b32 s86, s80
	s_mov_b32 s87, s80
	s_mov_b32 s88, s80
	s_mov_b32 s89, s80
	s_mov_b32 s90, s80
	s_waitcnt vmcnt(11)
	ds_write_b128 v187, v[0:3]
	s_waitcnt vmcnt(10)
	ds_write_b128 v187, v[4:7] offset:8192
	s_waitcnt vmcnt(9)
	ds_write_b128 v185, v[8:11] offset:32768
	s_waitcnt vmcnt(8)
	ds_write_b128 v185, v[12:15] offset:40960
	s_waitcnt lgkmcnt(0)
	s_barrier
	ds_read_b128 v[0:3], v189 offset:32768
	ds_read_b128 v[4:7], v189 offset:40960
	s_waitcnt vmcnt(7) lgkmcnt(1)
	v_mfma_f32_32x32x16_bf16 v[16:31], v[0:3], v[112:115], 0
	v_add_u32_e32 v0, 32, v180
	v_xad_u32 v0, v0, v66, v65
	v_add_u32_e32 v199, 0x8000, v0
	v_add_u32_e32 v8, 0xc0, v180
	v_xad_u32 v12, v8, v66, v65
	v_add_u32_e32 v201, 0x8000, v12
	v_lshlrev_b32_e32 v10, 1, v68
	s_waitcnt lgkmcnt(0)
	v_mfma_f32_32x32x16_bf16 v[32:47], v[4:7], v[112:115], 0
	ds_read_b128 v[0:3], v199 offset:32768
	ds_read_b128 v[4:7], v199 offset:40960
	s_mov_b32 s91, s80
	s_mov_b32 s92, s80
	s_mov_b32 s93, s80
	s_mov_b32 s94, s80
	s_mov_b32 s95, s80
	s_mov_b32 s50, 2
	s_waitcnt vmcnt(6) lgkmcnt(1)
	v_mfma_f32_32x32x16_bf16 v[16:31], v[0:3], v[108:111], v[16:31]
	v_add_u32_e32 v0, 64, v180
	v_xad_u32 v0, v0, v66, v65
	v_add_u32_e32 v192, 0x8000, v0
	v_lshl_add_u32 v181, v178, 2, s1
	v_mov_b32_e32 v182, 0
	s_waitcnt lgkmcnt(0)
	v_mfma_f32_32x32x16_bf16 v[32:47], v[4:7], v[108:111], v[32:47]
	ds_read_b128 v[0:3], v192 offset:32768
	ds_read_b128 v[4:7], v192 offset:40960
	s_waitcnt vmcnt(5) lgkmcnt(1)
	v_mfma_f32_32x32x16_bf16 v[16:31], v[0:3], v[120:123], v[16:31]
	v_add_u32_e32 v0, 0x60, v180
	v_xad_u32 v0, v0, v66, v65
	v_add_u32_e32 v191, 0x8000, v0
	s_waitcnt lgkmcnt(0)
	v_mfma_f32_32x32x16_bf16 v[32:47], v[4:7], v[120:123], v[32:47]
	ds_read_b128 v[0:3], v191 offset:32768
	ds_read_b128 v[4:7], v191 offset:40960
	s_waitcnt vmcnt(4) lgkmcnt(1)
	v_mfma_f32_32x32x16_bf16 v[16:31], v[0:3], v[124:127], v[16:31]
	v_add_u32_e32 v0, 0x80, v180
	v_xad_u32 v0, v0, v66, v65
	v_add_u32_e32 v190, 0x8000, v0
	ds_read_b128 v[0:3], v189 offset:32896
	s_waitcnt lgkmcnt(1)
	v_mfma_f32_32x32x16_bf16 v[32:47], v[4:7], v[124:127], v[32:47]
	ds_read_b128 v[4:7], v189 offset:41088
	s_waitcnt vmcnt(3) lgkmcnt(1)
	v_mfma_f32_32x32x16_bf16 v[16:31], v[0:3], v[116:119], v[16:31]
	v_and_b32_e32 v0, 0xc0, v48
	v_and_or_b32 v11, v64, 24, v0
	v_add_u32_e32 v0, 0xa0, v180
	v_xad_u32 v0, v0, v66, v65
	v_add_u32_e32 v198, 0x8000, v0
	ds_read_b128 v[0:3], v199 offset:32896
	s_waitcnt lgkmcnt(1)
; #define SLOAD(i, k0) do { sr_[i].vs0 = St::ld8(&Vh[(long)((k0) + sr) * LDK + sc]); sr_[i].vs1 = St::ld8(&Vh[(long)((k0) + 32 + sr) * LDK + sc]); \
;     sr_[i].ks0 = St::ld8(&Kh[(long)((k0) + sr) * LDK + sc]); sr_[i].ks1 = St::ld8(&Kh[(long)((k0) + 32 + sr) * LDK + sc]); } while (0)
; #define SWAIT() do { if constexpr (SDEPTH == 2) asm volatile("s_waitcnt vmcnt(4)" ::: "memory"); else asm volatile("s_waitcnt vmcnt(0)" ::: "memory"); } while (0)
; __device__ __forceinline__ void partialSM(f32x16& p0, f32x16& p1, float& m_reg, float& mn, float& alpha) {
;   constexpr float C = SCALE * 1.4426950408889634f;
;   float pmax = p0[0]; for (int r = 1; r < 16; ++r) pmax = fmaxf(pmax, p0[r]); for (int r = 0; r < 16; ++r) pmax = fmaxf(pmax, p1[r]);
;   { auto rr = __builtin_amdgcn_permlane32_swap(__float_as_uint(pmax), __float_as_uint(pmax), false, false);
;     pmax = fmaxf(__uint_as_float(rr[0]), __uint_as_float(rr[1])); }
;   if (__builtin_expect(__all(pmax - m_reg <= THR / SCALE), 1)) { mn = m_reg; alpha = 1.f; }
;   else { mn = fmaxf(m_reg, pmax); alpha = __builtin_amdgcn_exp2f((m_reg - mn) * C); m_reg = mn; }
;   float mnC = -mn * C;
;   for (int r = 0; r < 16; ++r) p0[r] = fmaf(p0[r], C, mnC); for (int r = 0; r < 16; ++r) p1[r] = fmaf(p1[r], C, mnC);
;   for (int r = 0; r < 16; ++r) p0[r] = __builtin_amdgcn_exp2f(p0[r]);
; template <typename TQ>
; __device__ __forceinline__ void attn_dense_body(const TQ* __restrict__ Qb, const bf16* __restrict__ Kh, const bf16* __restrict__ Vh,
;                                                 unsigned short* __restrict__ Ob, int seq, char* lds, const int wave_s) {
;     ...
;   qkt(pA0, pA1, K_lds, qr, r32, hi); partialSM(pA0, pA1, m_reg, mnA, alA);
;   SLOAD(SO, KVBLK); if constexpr (SDEPTH == 2) { if (2 < NT) SLOAD(SE, 2 * KVBLK); }
;   SWAIT(); SWRITE(1, SO); __syncthreads();
	v_mfma_f32_32x32x16_bf16 v[32:47], v[4:7], v[116:119], v[32:47]
	v_add_u32_e32 v4, 64, v69
	v_mad_i64_i32 v[4:5], s[46:47], v4, s97, 0
	v_or_b32_e32 v4, v4, v70
	v_lshl_add_u64 v[8:9], v[4:5], 1, s[38:39]
	ds_read_b128 v[4:7], v199 offset:41088
	global_load_dwordx4 v[48:51], v[8:9], off offset:2560
	s_waitcnt vmcnt(3) lgkmcnt(1)
	v_mfma_f32_32x32x16_bf16 v[16:31], v[0:3], v[104:107], v[16:31]
	v_add_u32_e32 v0, 0x60, v69
	v_mad_i64_i32 v[0:1], s[46:47], v0, s97, 0
	v_or_b32_e32 v0, v0, v70
	v_lshl_add_u64 v[0:1], v[0:1], 1, s[38:39]
	global_load_dwordx4 v[52:55], v[0:1], off offset:2560
	global_load_dwordx4 v[56:59], v[8:9], off offset:2048
	global_load_dwordx4 v[60:63], v[0:1], off offset:2048
	ds_read_b128 v[0:3], v192 offset:32896
	s_waitcnt lgkmcnt(1)
	v_mfma_f32_32x32x16_bf16 v[32:47], v[4:7], v[104:107], v[32:47]
	v_and_b32_e32 v4, 32, v10
	v_and_b32_e32 v5, 0x100, v64
	v_or3_b32 v71, v11, v4, v5
	ds_read_b128 v[4:7], v192 offset:41088
	v_add_u32_e32 v184, s51, v71
	s_waitcnt vmcnt(5) lgkmcnt(1)
	v_mfma_f32_32x32x16_bf16 v[16:31], v[0:3], v[100:103], v[16:31]
	v_add_u32_e32 v0, 0xe0, v180
	v_xad_u32 v0, v0, v66, v65
	v_add_u32_e32 v200, 0x8000, v0
	ds_read_b128 v[0:3], v191 offset:32896
	ds_read_b128 v[64:67], v191 offset:41088
	s_waitcnt lgkmcnt(2)
	v_mfma_f32_32x32x16_bf16 v[32:47], v[4:7], v[100:103], v[32:47]
	s_waitcnt vmcnt(4) lgkmcnt(1)
	v_mfma_f32_32x32x16_bf16 v[16:31], v[0:3], v[96:99], v[16:31]
	v_mov_b64_e32 v[0:1], s[80:81]
	v_mov_b64_e32 v[14:15], s[94:95]
	v_mov_b64_e32 v[2:3], s[82:83]
	v_mov_b64_e32 v[4:5], s[84:85]
	v_mov_b64_e32 v[6:7], s[86:87]
	v_mov_b64_e32 v[8:9], s[88:89]
	v_mov_b64_e32 v[10:11], s[90:91]
	s_waitcnt lgkmcnt(0)
	v_mfma_f32_32x32x16_bf16 v[32:47], v[64:67], v[96:99], v[32:47]
	s_nop 2
	v_max_f32_e32 v64, v17, v17
	v_max_f32_e32 v65, v16, v16
	v_max_f32_e32 v64, v65, v64
	v_max3_f32 v64, v64, v18, v19
	v_max3_f32 v64, v64, v20, v21
	v_max3_f32 v64, v64, v22, v23
	v_max3_f32 v64, v64, v24, v25
	v_max3_f32 v64, v64, v26, v27
	v_max3_f32 v64, v64, v28, v29
	v_max3_f32 v64, v64, v30, v31
	v_max3_f32 v64, v64, v32, v33
	v_max3_f32 v64, v64, v34, v35
	v_max3_f32 v64, v64, v36, v37
	v_max3_f32 v64, v64, v38, v39
	v_max3_f32 v64, v64, v40, v41
	v_max3_f32 v64, v64, v42, v43
	v_max3_f32 v64, v64, v44, v45
	v_max3_f32 v64, v64, v46, v47
	v_mov_b32_e32 v65, v64
	s_nop 1
	v_permlane32_swap_b32_e32 v64, v65
	v_max_f32_e32 v73, v64, v64
	v_add_u32_e32 v64, 0x80, v69
	v_max_f32_e32 v72, v65, v65
	v_mad_i64_i32 v[64:65], s[46:47], v64, s97, 0
	v_add_u32_e32 v66, 0xa0, v69
	v_or_b32_e32 v64, v64, v70
	v_mad_i64_i32 v[66:67], s[46:47], v66, s97, 0
	v_lshl_add_u64 v[64:65], v[64:65], 1, s[38:39]
	v_or_b32_e32 v66, v66, v70
	v_lshl_add_u64 v[66:67], v[66:67], 1, s[38:39]
	global_load_dwordx4 v[128:131], v[64:65], off offset:2560
	global_load_dwordx4 v[132:135], v[64:65], off offset:2048
	global_load_dwordx4 v[136:139], v[66:67], off offset:2560
	global_load_dwordx4 v[140:143], v[66:67], off offset:2048
	v_max_f32_e32 v64, v73, v72
	s_waitcnt vmcnt(4)
	s_waitcnt vmcnt(7)
	ds_write_b128 v187, v[48:51] offset:16384
	s_waitcnt vmcnt(6)
	ds_write_b128 v187, v[52:55] offset:24576
	s_waitcnt vmcnt(5)
	ds_write_b128 v185, v[56:59] offset:49152
	s_waitcnt vmcnt(4)
	ds_write_b128 v185, v[60:63] offset:57344
	v_xor_b32_e32 v185, 0x18000, v185
	v_xor_b32_e32 v187, 0x8000, v187
	v_max_f32_e32 v48, 0xf149f2ca, v64
	v_sub_f32_e32 v49, 0xf149f2ca, v48
	v_mul_f32_e32 v49, 0x3e0293ee, v49
	v_add_f32_e32 v65, 0x7149f2ca, v64
	v_exp_f32_e32 v49, v49
	v_cmp_ge_f32_e32 vcc, s9, v65
	s_cmp_eq_u64 vcc, exec
	s_cselect_b64 vcc, -1, 0
	v_cndmask_b32_e64 v202, v49, 1.0, vcc
	v_mov_b32_e32 v49, 0xf149f2ca
	v_cndmask_b32_e32 v164, v48, v49, vcc
	v_mul_f32_e32 v48, 0xbe0293ee, v164
	v_fmamk_f32 v16, v16, 0x3e0293ee, v48
	v_exp_f32_e32 v161, v16
	v_fmamk_f32 v16, v17, 0x3e0293ee, v48
	v_exp_f32_e32 v175, v16
	v_fmamk_f32 v16, v18, 0x3e0293ee, v48
	v_exp_f32_e32 v162, v16
	v_fmamk_f32 v16, v19, 0x3e0293ee, v48
	v_exp_f32_e32 v206, v16
	v_fmamk_f32 v16, v20, 0x3e0293ee, v48
	v_exp_f32_e32 v174, v16
	v_fmamk_f32 v16, v21, 0x3e0293ee, v48
	v_exp_f32_e32 v209, v16
	v_fmamk_f32 v16, v22, 0x3e0293ee, v48
	v_exp_f32_e32 v163, v16
	v_fmamk_f32 v16, v23, 0x3e0293ee, v48
	v_exp_f32_e32 v173, v16
	v_fmamk_f32 v16, v24, 0x3e0293ee, v48
	v_exp_f32_e32 v169, v16
	v_fmamk_f32 v16, v25, 0x3e0293ee, v48
	v_exp_f32_e32 v171, v16
	v_fmamk_f32 v16, v26, 0x3e0293ee, v48
	v_exp_f32_e32 v170, v16
	v_fmamk_f32 v16, v27, 0x3e0293ee, v48
	s_addk_i32 s51, 0x4000
	v_exp_f32_e32 v172, v16
	v_fmamk_f32 v16, v28, 0x3e0293ee, v48
	s_add_u32 s40, s40, s44
	v_exp_f32_e32 v165, v16
	v_fmamk_f32 v16, v29, 0x3e0293ee, v48
	s_addc_u32 s41, s41, s45
	v_pk_fma_f32 v[144:145], v[46:47], s[30:31], v[48:49] op_sel_hi:[1,0,0]
	v_pk_fma_f32 v[150:151], v[44:45], s[30:31], v[48:49] op_sel_hi:[1,0,0]
	v_pk_fma_f32 v[154:155], v[42:43], s[30:31], v[48:49] op_sel_hi:[1,0,0]
	v_pk_fma_f32 v[146:147], v[40:41], s[30:31], v[48:49] op_sel_hi:[1,0,0]
	v_pk_fma_f32 v[148:149], v[38:39], s[30:31], v[48:49] op_sel_hi:[1,0,0]
	v_pk_fma_f32 v[152:153], v[36:37], s[30:31], v[48:49] op_sel_hi:[1,0,0]
	v_pk_fma_f32 v[156:157], v[34:35], s[30:31], v[48:49] op_sel_hi:[1,0,0]
	v_pk_fma_f32 v[158:159], v[32:33], s[30:31], v[48:49] op_sel_hi:[1,0,0]
	v_exp_f32_e32 v167, v16
	v_fmamk_f32 v16, v30, 0x3e0293ee, v48
	v_fmac_f32_e32 v48, 0x3e0293ee, v31
	s_lshl_b64 s[40:41], s[40:41], 1
	v_readlane_b32 s44, v255, 53
	v_exp_f32_e32 v166, v16
	v_exp_f32_e32 v168, v48
	v_mad_i64_i32 v[16:17], s[46:47], v69, s33, 0
	v_and_b32_e32 v18, 15, v68
	s_add_u32 s40, s44, s40
	v_readlane_b32 s44, v255, 54
	v_lshl_or_b32 v16, v18, 4, v16
	s_addc_u32 s41, s44, s41
	v_mov_b64_e32 v[12:13], s[92:93]
	v_mov_b32_e32 v176, v16
	v_add_u32_e32 v177, 0x18000, v16
	v_add_u32_e32 v198, 0x30000, v16
	v_add_u32_e32 v200, 0x48000, v16
	s_add_u32 s52, s40, 0xfffb8000
	s_addc_u32 s53, s41, -1
	v_mov_b64_e32 v[62:63], v[14:15]
	v_mov_b64_e32 v[46:47], v[14:15]
	v_mov_b64_e32 v[30:31], v[14:15]
	v_cmp_gt_u32_e64 s[38:39], 32, v68
	v_add_u32_e32 v183, s51, v71
	v_mov_b64_e32 v[60:61], v[12:13]
	v_mov_b64_e32 v[58:59], v[10:11]
	v_mov_b64_e32 v[56:57], v[8:9]
	v_mov_b64_e32 v[54:55], v[6:7]
	v_mov_b64_e32 v[52:53], v[4:5]
	v_mov_b64_e32 v[50:51], v[2:3]
	v_mov_b64_e32 v[48:49], v[0:1]
	v_mov_b64_e32 v[44:45], v[12:13]
	v_mov_b64_e32 v[42:43], v[10:11]
	v_mov_b64_e32 v[40:41], v[8:9]
	v_mov_b64_e32 v[38:39], v[6:7]
	v_mov_b64_e32 v[36:37], v[4:5]
	v_mov_b64_e32 v[34:35], v[2:3]
	v_mov_b64_e32 v[32:33], v[0:1]
	v_mov_b64_e32 v[28:29], v[12:13]
	v_mov_b64_e32 v[26:27], v[10:11]
	v_mov_b64_e32 v[24:25], v[8:9]
	v_mov_b64_e32 v[22:23], v[6:7]
	v_mov_b64_e32 v[20:21], v[4:5]
	v_mov_b64_e32 v[18:19], v[2:3]
	v_mov_b64_e32 v[16:17], v[0:1]
	s_mov_b64 s[94:95], s[16:17]
	s_mov_b64 s[84:85], s[12:13]
	s_waitcnt lgkmcnt(0)
	s_barrier
; #define SBAR() __builtin_amdgcn_sched_barrier(0)
; #define SLOAD(i, k0) do { sr_[i].vs0 = St::ld8(&Vh[(long)((k0) + sr) * LDK + sc]); sr_[i].vs1 = St::ld8(&Vh[(long)((k0) + 32 + sr) * LDK + sc]); \
;     sr_[i].ks0 = St::ld8(&Kh[(long)((k0) + sr) * LDK + sc]); sr_[i].ks1 = St::ld8(&Kh[(long)((k0) + 32 + sr) * LDK + sc]); } while (0)
; __device__ __forceinline__ void finishSM(f32x16& p0, f32x16& p1, float alpha, float& l_reg, bf16x8& pa0, bf16x8& pa1, bf16x8& pa2, bf16x8& pa3) {
;   for (int r = 0; r < 16; ++r) p1[r] = __builtin_amdgcn_exp2f(p1[r]);
;   float ps = 0; for (int r = 0; r < 16; ++r) ps += p0[r]; for (int r = 0; r < 16; ++r) ps += p1[r];
;   { auto rr = __builtin_amdgcn_permlane32_swap(__float_as_uint(ps), __float_as_uint(ps), false, false);
;     ps = __uint_as_float(rr[0]) + __uint_as_float(rr[1]); }
;   l_reg = l_reg * alpha + ps;
;     ...
;   PK4(p0, 0, pa0); PK4(p0, 8, pa1); PK4(p1, 0, pa2); PK4(p1, 8, pa3);
; template <typename TQ>
; __device__ __forceinline__ void attn_dense_body(const TQ* __restrict__ Qb, const bf16* __restrict__ Kh, const bf16* __restrict__ Vh,
;                                                 unsigned short* __restrict__ Ob, int seq, char* lds, const int wave_s) {
;     ...
;     SBAR(); qkt(pB0, pB1, (bf16*)((char*)K_lds + SHM_K), qr, r32, hi);
;     finishSM(pA0, pA1, alA, l_reg, pa0, pa1, pa2, pa3); SBAR();
;     SLOAD(SO, (j + SDEPTH) * KVBLK); SBAR();
;     pv_d0(o, vb0, pa0, pa1, pa2, pa3); partialSM(pB0, pB1, m_reg, mnB, alB);
.LBB0_575:
	ds_read_b128 v[64:67], v189 offset:49152
	ds_read_b128 v[68:71], v189 offset:57344
	ds_read_b128 v[210:213], v199 offset:49152
	ds_read_b128 v[214:217], v199 offset:57344
	ds_read_b128 v[240:243], v192 offset:49152
	ds_read_b128 v[244:247], v192 offset:57344
	v_add_f32_e32 v160, v175, v161
	s_waitcnt lgkmcnt(5)
	v_mfma_f32_32x32x16_bf16 v[80:95], v[64:67], v[112:115], 0
	v_add_f32_e32 v160, v162, v160
	v_add_f32_e32 v160, v206, v160
	v_add_f32_e32 v160, v174, v160
	v_add_f32_e32 v160, v209, v160
	v_add_f32_e32 v160, v163, v160
	v_add_f32_e32 v160, v173, v160
	v_add_f32_e32 v160, v169, v160
	s_waitcnt lgkmcnt(4)
	v_mfma_f32_32x32x16_bf16 v[64:79], v[68:71], v[112:115], 0
	v_add_f32_e32 v160, v171, v160
	v_add_f32_e32 v160, v170, v160
	v_add_f32_e32 v160, v172, v160
	v_exp_f32_e32 v158, v158
	v_add_f32_e32 v160, v165, v160
	v_exp_f32_e32 v159, v159
	v_add_f32_e32 v160, v167, v160
	s_waitcnt lgkmcnt(3)
	v_mfma_f32_32x32x16_bf16 v[80:95], v[210:213], v[108:111], v[80:95]
	v_exp_f32_e32 v156, v156
	v_add_f32_e32 v160, v166, v160
	v_exp_f32_e32 v157, v157
	v_add_f32_e32 v160, v168, v160
	v_exp_f32_e32 v152, v152
	v_add_f32_e32 v160, v158, v160
	v_exp_f32_e32 v153, v153
	s_waitcnt lgkmcnt(2)
	v_mfma_f32_32x32x16_bf16 v[64:79], v[214:217], v[108:111], v[64:79]
	ds_read_b128 v[210:213], v191 offset:49152
	ds_read_b128 v[214:217], v191 offset:57344
	v_add_f32_e32 v160, v159, v160
	v_exp_f32_e32 v148, v148
	v_add_f32_e32 v160, v156, v160
	v_exp_f32_e32 v149, v149
	v_add_f32_e32 v160, v157, v160
	v_exp_f32_e32 v146, v146
	s_waitcnt lgkmcnt(3)
	v_mfma_f32_32x32x16_bf16 v[80:95], v[240:243], v[120:123], v[80:95]
	v_add_f32_e32 v160, v152, v160
	v_exp_f32_e32 v147, v147
	v_add_f32_e32 v160, v153, v160
	v_exp_f32_e32 v154, v154
	v_add_f32_e32 v160, v148, v160
	v_exp_f32_e32 v155, v155
	v_add_f32_e32 v160, v149, v160
	s_waitcnt lgkmcnt(2)
	v_mfma_f32_32x32x16_bf16 v[64:79], v[244:247], v[120:123], v[64:79]
	ds_read_b128 v[240:243], v189 offset:49280
	ds_read_b128 v[244:247], v189 offset:57472
	v_exp_f32_e32 v150, v150
	v_add_f32_e32 v160, v146, v160
	v_exp_f32_e32 v151, v151
	v_add_f32_e32 v160, v147, v160
	v_exp_f32_e32 v144, v144
	v_add_f32_e32 v160, v154, v160
	s_waitcnt lgkmcnt(3)
	v_mfma_f32_32x32x16_bf16 v[80:95], v[210:213], v[124:127], v[80:95]
	v_exp_f32_e32 v145, v145
	v_add_f32_e32 v160, v155, v160
	v_add_f32_e32 v160, v150, v160
	v_add_f32_e32 v160, v151, v160
	v_add_f32_e32 v160, v144, v160
	v_add_f32_e32 v203, v145, v160
	s_waitcnt lgkmcnt(2)
	v_mfma_f32_32x32x16_bf16 v[64:79], v[214:217], v[124:127], v[64:79]
	ds_read_b128 v[210:213], v199 offset:49280
	ds_read_b128 v[214:217], v199 offset:57472
	s_waitcnt lgkmcnt(3)
	v_mfma_f32_32x32x16_bf16 v[80:95], v[240:243], v[116:119], v[80:95]
	s_waitcnt lgkmcnt(2)
	v_mfma_f32_32x32x16_bf16 v[64:79], v[244:247], v[116:119], v[64:79]
	ds_read_b128 v[240:243], v192 offset:49280
	ds_read_b128 v[244:247], v192 offset:57472
	s_waitcnt lgkmcnt(3)
	v_mfma_f32_32x32x16_bf16 v[80:95], v[210:213], v[104:107], v[80:95]
	s_waitcnt lgkmcnt(2)
	v_mfma_f32_32x32x16_bf16 v[64:79], v[214:217], v[104:107], v[64:79]
	ds_read_b128 v[210:213], v191 offset:49280
	ds_read_b128 v[214:217], v191 offset:57472
	s_waitcnt lgkmcnt(3)
	v_mfma_f32_32x32x16_bf16 v[80:95], v[240:243], v[100:103], v[80:95]
	s_waitcnt lgkmcnt(2)
	v_mfma_f32_32x32x16_bf16 v[64:79], v[244:247], v[100:103], v[64:79]
	v_cvt_pk_bf16_f32 v160, v161, v175
	v_cvt_pk_bf16_f32 v161, v162, v206
	v_cvt_pk_bf16_f32 v162, v174, v209
	v_cvt_pk_bf16_f32 v163, v163, v173
	v_cvt_pk_bf16_f32 v206, v169, v171
	v_cvt_pk_bf16_f32 v207, v170, v172
	s_waitcnt lgkmcnt(1)
	v_mfma_f32_32x32x16_bf16 v[80:95], v[210:213], v[96:99], v[80:95]
	v_cvt_pk_bf16_f32 v208, v165, v167
	v_cvt_pk_bf16_f32 v209, v166, v168
	v_cvt_pk_bf16_f32 v166, v158, v159
	v_cvt_pk_bf16_f32 v167, v156, v157
	v_cvt_pk_bf16_f32 v168, v152, v153
	s_waitcnt lgkmcnt(0)
	v_mfma_f32_32x32x16_bf16 v[64:79], v[214:217], v[96:99], v[64:79]
	v_cvt_pk_bf16_f32 v169, v148, v149
	v_cvt_pk_bf16_f32 v170, v146, v147
	v_cvt_pk_bf16_f32 v171, v154, v155
	v_cvt_pk_bf16_f32 v172, v150, v151
	v_cvt_pk_bf16_f32 v173, v144, v145
	global_load_dwordx4 v[144:147], v176, s[52:53]
	global_load_dwordx4 v[148:151], v176, s[52:53] offset:-512
	global_load_dwordx4 v[156:159], v177, s[52:53]
	global_load_dwordx4 v[152:155], v177, s[52:53] offset:-512
	ds_read_b64_tr_b16 v[210:211], v184 offset:0
	ds_read_b64_tr_b16 v[212:213], v184 offset:0x800
	ds_read_b64_tr_b16 v[214:215], v184 offset:0x1000
	ds_read_b64_tr_b16 v[216:217], v184 offset:0x1800
	ds_read_b64_tr_b16 v[224:225], v184 offset:0x2000
	ds_read_b64_tr_b16 v[226:227], v184 offset:0x2800
	ds_read_b64_tr_b16 v[228:229], v184 offset:0x3000
	ds_read_b64_tr_b16 v[230:231], v184 offset:0x3800
	s_waitcnt lgkmcnt(0)
	v_mfma_f32_32x32x16_bf16 v[0:15], v[160:163], v[210:213], v[0:15]
	ds_read_b64_tr_b16 v[210:211], v184 offset:0x200
	ds_read_b64_tr_b16 v[212:213], v184 offset:0xa00
	v_mfma_f32_32x32x16_bf16 v[0:15], v[206:209], v[214:217], v[0:15]
	ds_read_b64_tr_b16 v[214:215], v184 offset:0x1200
	ds_read_b64_tr_b16 v[216:217], v184 offset:0x1a00
	v_mfma_f32_32x32x16_bf16 v[0:15], v[166:169], v[224:227], v[0:15]
	ds_read_b64_tr_b16 v[224:225], v184 offset:0x2200
	ds_read_b64_tr_b16 v[226:227], v184 offset:0x2a00
	v_mfma_f32_32x32x16_bf16 v[0:15], v[170:173], v[228:231], v[0:15]
	ds_read_b64_tr_b16 v[228:229], v184 offset:0x3200
	ds_read_b64_tr_b16 v[230:231], v184 offset:0x3a00
	s_waitcnt lgkmcnt(0)
; #define SBAR() __builtin_amdgcn_sched_barrier(0)
; __device__ __forceinline__ void partialSM(f32x16& p0, f32x16& p1, float& m_reg, float& mn, float& alpha) {
;   constexpr float C = SCALE * 1.4426950408889634f;
;   float pmax = p0[0]; for (int r = 1; r < 16; ++r) pmax = fmaxf(pmax, p0[r]); for (int r = 0; r < 16; ++r) pmax = fmaxf(pmax, p1[r]);
;   { auto rr = __builtin_amdgcn_permlane32_swap(__float_as_uint(pmax), __float_as_uint(pmax), false, false);
;     pmax = fmaxf(__uint_as_float(rr[0]), __uint_as_float(rr[1])); }
;   if (__builtin_expect(__all(pmax - m_reg <= THR / SCALE), 1)) { mn = m_reg; alpha = 1.f; }
; template <int D0> __device__ __forceinline__ void pv_one(f32x16& od, int vb, bf16x8 pa0, bf16x8 pa1, bf16x8 pa2, bf16x8 pa3) {
;   const s16x4 l0 = tr_read<v_rd_off(D0, 0, 0)>(vb), h0 = tr_read<v_rd_off(D0, 0, 1)>(vb), l1 = tr_read<v_rd_off(D0, 1, 0)>(vb), h1 = tr_read<v_rd_off(D0, 1, 1)>(vb);
;   const s16x4 l2 = tr_read<v_rd_off(D0, 2, 0)>(vb), h2 = tr_read<v_rd_off(D0, 2, 1)>(vb), l3 = tr_read<v_rd_off(D0, 3, 0)>(vb), h3 = tr_read<v_rd_off(D0, 3, 1)>(vb);
;   asm volatile("s_waitcnt lgkmcnt(0)" ::: "memory"); SBAR();
;     ...
;   od = __builtin_amdgcn_mfma_f32_32x32x16_bf16(pa0, PK(l0, h0), od, 0, 0, 0);
;   od = __builtin_amdgcn_mfma_f32_32x32x16_bf16(pa1, PK(l1, h1), od, 0, 0, 0);
;   od = __builtin_amdgcn_mfma_f32_32x32x16_bf16(pa2, PK(l2, h2), od, 0, 0, 0);
;   od = __builtin_amdgcn_mfma_f32_32x32x16_bf16(pa3, PK(l3, h3), od, 0, 0, 0);
;     ...
; }
; __device__ __forceinline__ void pv_d0(f32x16* o, int vb, bf16x8 pa0, bf16x8 pa1, bf16x8 pa2, bf16x8 pa3) {
;   pv_one<0>(o[0], vb, pa0, pa1, pa2, pa3); pv_one<1>(o[1], vb, pa0, pa1, pa2, pa3); pv_one<2>(o[2], vb, pa0, pa1, pa2, pa3); pv_one<3>(o[3], vb, pa0, pa1, pa2, pa3);
	v_mfma_f32_32x32x16_bf16 v[48:63], v[160:163], v[210:213], v[48:63]
	ds_read_b64_tr_b16 v[210:211], v184 offset:0x400
	ds_read_b64_tr_b16 v[212:213], v184 offset:0xc00
	v_mfma_f32_32x32x16_bf16 v[48:63], v[206:209], v[214:217], v[48:63]
	ds_read_b64_tr_b16 v[214:215], v184 offset:0x1400
	ds_read_b64_tr_b16 v[216:217], v184 offset:0x1c00
	v_mfma_f32_32x32x16_bf16 v[48:63], v[166:169], v[224:227], v[48:63]
	ds_read_b64_tr_b16 v[224:225], v184 offset:0x2400
	ds_read_b64_tr_b16 v[226:227], v184 offset:0x2c00
	v_mfma_f32_32x32x16_bf16 v[48:63], v[170:173], v[228:231], v[48:63]
	ds_read_b64_tr_b16 v[228:229], v184 offset:0x3400
	ds_read_b64_tr_b16 v[230:231], v184 offset:0x3c00
	s_waitcnt lgkmcnt(0)
	v_mfma_f32_32x32x16_bf16 v[32:47], v[160:163], v[210:213], v[32:47]
	ds_read_b64_tr_b16 v[210:211], v184 offset:0x600
	ds_read_b64_tr_b16 v[212:213], v184 offset:0xe00
	v_mfma_f32_32x32x16_bf16 v[32:47], v[206:209], v[214:217], v[32:47]
	ds_read_b64_tr_b16 v[214:215], v184 offset:0x1600
	ds_read_b64_tr_b16 v[216:217], v184 offset:0x1e00
	v_mfma_f32_32x32x16_bf16 v[32:47], v[166:169], v[224:227], v[32:47]
	ds_read_b64_tr_b16 v[224:225], v184 offset:0x2600
	ds_read_b64_tr_b16 v[226:227], v184 offset:0x2e00
	v_mfma_f32_32x32x16_bf16 v[32:47], v[170:173], v[228:231], v[32:47]
	ds_read_b64_tr_b16 v[228:229], v184 offset:0x3600
	ds_read_b64_tr_b16 v[230:231], v184 offset:0x3e00
	s_waitcnt lgkmcnt(0)
	v_mfma_f32_32x32x16_bf16 v[16:31], v[160:163], v[210:213], v[16:31]
	v_max_f32_e32 v160, v80, v81
	v_max3_f32 v160, v160, v82, v83
	v_max3_f32 v160, v160, v84, v85
	v_max3_f32 v160, v160, v86, v87
	v_max3_f32 v160, v160, v88, v89
	v_max3_f32 v160, v160, v90, v91
	v_max3_f32 v160, v160, v92, v93
	v_mfma_f32_32x32x16_bf16 v[16:31], v[206:209], v[214:217], v[16:31]
	v_max3_f32 v160, v160, v94, v95
	v_max3_f32 v160, v160, v64, v65
	v_max3_f32 v160, v160, v66, v67
	v_max3_f32 v160, v160, v68, v69
	v_max3_f32 v160, v160, v70, v71
	v_max3_f32 v160, v160, v72, v73
	v_max3_f32 v160, v160, v74, v75
	v_max3_f32 v160, v160, v76, v77
	v_mfma_f32_32x32x16_bf16 v[16:31], v[166:169], v[224:227], v[16:31]
	v_max3_f32 v160, v160, v78, v79
	v_mov_b32_e32 v161, v160
	s_nop 1
	v_permlane32_swap_b32_e32 v160, v161
	v_max_f32_e32 v160, v160, v161
	v_sub_f32_e32 v161, v160, v164
	v_cmp_ge_f32_e32 vcc, s9, v161
	v_mfma_f32_32x32x16_bf16 v[16:31], v[170:173], v[228:231], v[16:31]
	s_cmp_eq_u64 vcc, exec
	s_cbranch_scc0 .Lattn_slow_a
	v_mov_b32_e32 v205, 1.0
	v_mov_b32_e32 v206, v164
	s_waitcnt vmcnt(4)
	ds_write_b128 v187, v[128:131]
	ds_write_b128 v187, v[136:139] offset:8192
	ds_write_b128 v185, v[132:135] offset:32768
	ds_write_b128 v185, v[140:143] offset:40960
; #define SBAR() __builtin_amdgcn_sched_barrier(0)
; #define SLOAD(i, k0) do { sr_[i].vs0 = St::ld8(&Vh[(long)((k0) + sr) * LDK + sc]); sr_[i].vs1 = St::ld8(&Vh[(long)((k0) + 32 + sr) * LDK + sc]); \
;     sr_[i].ks0 = St::ld8(&Kh[(long)((k0) + sr) * LDK + sc]); sr_[i].ks1 = St::ld8(&Kh[(long)((k0) + 32 + sr) * LDK + sc]); } while (0)
; #define RESC(a) do { if (__any((a) < 1.f)) { if (hi == 0) al_l[r32] = (a); asm volatile("s_waitcnt lgkmcnt(0)" ::: "memory"); \
;     for (int d = 0; d < 4; ++d) for (int r = 0; r < 16; ++r) o[d][r] *= al_l[crow(r, hi)]; } } while (0)
; __device__ __forceinline__ void partialSM(f32x16& p0, f32x16& p1, float& m_reg, float& mn, float& alpha) {
;     ...
;   float mnC = -mn * C;
;   for (int r = 0; r < 16; ++r) p0[r] = fmaf(p0[r], C, mnC); for (int r = 0; r < 16; ++r) p1[r] = fmaf(p1[r], C, mnC);
;   for (int r = 0; r < 16; ++r) p0[r] = __builtin_amdgcn_exp2f(p0[r]);
; }
; __device__ __forceinline__ void finishSM(f32x16& p0, f32x16& p1, float alpha, float& l_reg, bf16x8& pa0, bf16x8& pa1, bf16x8& pa2, bf16x8& pa3) {
;   for (int r = 0; r < 16; ++r) p1[r] = __builtin_amdgcn_exp2f(p1[r]);
;   float ps = 0; for (int r = 0; r < 16; ++r) ps += p0[r]; for (int r = 0; r < 16; ++r) ps += p1[r];
;   { auto rr = __builtin_amdgcn_permlane32_swap(__float_as_uint(ps), __float_as_uint(ps), false, false);
;     ps = __uint_as_float(rr[0]) + __uint_as_float(rr[1]); }
;   l_reg = l_reg * alpha + ps;
;     ...
;   PK4(p0, 0, pa0); PK4(p0, 8, pa1); PK4(p1, 0, pa2); PK4(p1, 8, pa3);
; template <typename TQ>
; __device__ __forceinline__ void attn_dense_body(const TQ* __restrict__ Qb, const bf16* __restrict__ Kh, const bf16* __restrict__ Vh,
;                                                 unsigned short* __restrict__ Ob, int seq, char* lds, const int wave_s) {
;     ...
;     RESC(alB); __syncthreads();
;     SBAR(); qkt(pA0, pA1, K_lds, qr, r32, hi);
;     finishSM(pB0, pB1, alB, l_reg, pa0, pa1, pa2, pa3); SBAR();
;     if (SDEPTH == 1 || j + 3 < NT) SLOAD(SE, (j + 1 + SDEPTH) * KVBLK); SBAR();
.LBB0_579:
	v_xor_b32_e32 v189, 0x18000, v189
	v_xor_b32_e32 v199, 0x18000, v199
	v_xor_b32_e32 v192, 0x18000, v192
	v_xor_b32_e32 v191, 0x18000, v191
	v_mul_f32_e32 v207, 0xbe0293ee, v206
	v_fmamk_f32 v80, v80, 0x3e0293ee, v207
	v_fmamk_f32 v81, v81, 0x3e0293ee, v207
	v_fmamk_f32 v82, v82, 0x3e0293ee, v207
	v_fmamk_f32 v83, v83, 0x3e0293ee, v207
	v_fmamk_f32 v84, v84, 0x3e0293ee, v207
	v_fmamk_f32 v85, v85, 0x3e0293ee, v207
	v_fmamk_f32 v86, v86, 0x3e0293ee, v207
	v_fmamk_f32 v87, v87, 0x3e0293ee, v207
	v_fmamk_f32 v88, v88, 0x3e0293ee, v207
	v_fmamk_f32 v89, v89, 0x3e0293ee, v207
	v_fmamk_f32 v90, v90, 0x3e0293ee, v207
	v_fmamk_f32 v91, v91, 0x3e0293ee, v207
	v_fmamk_f32 v92, v92, 0x3e0293ee, v207
	v_fmamk_f32 v93, v93, 0x3e0293ee, v207
	v_fmamk_f32 v94, v94, 0x3e0293ee, v207
	v_fmamk_f32 v95, v95, 0x3e0293ee, v207
	v_exp_f32_e32 v160, v80
	v_exp_f32_e32 v175, v81
	v_exp_f32_e32 v161, v82
	v_exp_f32_e32 v174, v83
	v_exp_f32_e32 v162, v84
	v_exp_f32_e32 v173, v85
	v_exp_f32_e32 v163, v86
	v_exp_f32_e32 v172, v87
	v_exp_f32_e32 v164, v88
	v_exp_f32_e32 v171, v89
	v_exp_f32_e32 v165, v90
	v_exp_f32_e32 v170, v91
	v_exp_f32_e32 v166, v92
	v_exp_f32_e32 v169, v93
	v_exp_f32_e32 v167, v94
	v_exp_f32_e32 v168, v95
	v_fmamk_f32 v216, v64, 0x3e0293ee, v207
	v_fmamk_f32 v217, v65, 0x3e0293ee, v207
	v_fmamk_f32 v218, v66, 0x3e0293ee, v207
	v_fmamk_f32 v219, v67, 0x3e0293ee, v207
	v_fmamk_f32 v224, v68, 0x3e0293ee, v207
	v_fmamk_f32 v209, v69, 0x3e0293ee, v207
	v_fmamk_f32 v210, v70, 0x3e0293ee, v207
	v_fmamk_f32 v211, v71, 0x3e0293ee, v207
	v_fmamk_f32 v212, v72, 0x3e0293ee, v207
	v_fmamk_f32 v213, v73, 0x3e0293ee, v207
	v_fmamk_f32 v214, v74, 0x3e0293ee, v207
	v_fmamk_f32 v215, v75, 0x3e0293ee, v207
	v_fmamk_f32 v208, v76, 0x3e0293ee, v207
	v_fmamk_f32 v225, v77, 0x3e0293ee, v207
	v_fmamk_f32 v226, v78, 0x3e0293ee, v207
	v_fmac_f32_e32 v207, 0x3e0293ee, v79
	s_waitcnt lgkmcnt(0)
	s_barrier
	ds_read_b128 v[64:67], v189 offset:32768
	ds_read_b128 v[68:71], v189 offset:40960
	ds_read_b128 v[228:231], v199 offset:32768
	ds_read_b128 v[232:235], v199 offset:40960
	ds_read_b128 v[240:243], v192 offset:32768
	ds_read_b128 v[244:247], v192 offset:40960
	v_exp_f32_e32 v221, v207
	s_waitcnt lgkmcnt(5)
	v_mfma_f32_32x32x16_bf16 v[80:95], v[64:67], v[112:115], 0
	v_add_f32_e32 v207, v175, v160
	v_add_f32_e32 v207, v161, v207
	v_add_f32_e32 v207, v174, v207
	v_add_f32_e32 v207, v162, v207
	v_add_f32_e32 v207, v173, v207
	v_add_f32_e32 v207, v163, v207
	v_add_f32_e32 v207, v172, v207
	s_waitcnt lgkmcnt(4)
	v_mfma_f32_32x32x16_bf16 v[64:79], v[68:71], v[112:115], 0
	v_add_f32_e32 v207, v164, v207
	v_add_f32_e32 v207, v171, v207
	v_add_f32_e32 v207, v165, v207
	v_add_f32_e32 v207, v170, v207
	v_exp_f32_e32 v194, v216
	v_add_f32_e32 v207, v166, v207
	v_exp_f32_e32 v195, v217
	s_waitcnt lgkmcnt(3)
	v_mfma_f32_32x32x16_bf16 v[80:95], v[228:231], v[108:111], v[80:95]
	v_add_f32_e32 v207, v169, v207
	v_exp_f32_e32 v196, v218
	v_add_f32_e32 v207, v167, v207
	v_exp_f32_e32 v197, v219
	v_add_f32_e32 v207, v168, v207
	v_exp_f32_e32 v216, v224
	v_add_f32_e32 v207, v194, v207
	s_waitcnt lgkmcnt(2)
	v_mfma_f32_32x32x16_bf16 v[64:79], v[232:235], v[108:111], v[64:79]
	ds_read_b128 v[228:231], v191 offset:32768
	ds_read_b128 v[232:235], v191 offset:40960
	v_exp_f32_e32 v209, v209
	v_add_f32_e32 v207, v195, v207
	v_exp_f32_e32 v210, v210
	v_add_f32_e32 v207, v196, v207
	v_exp_f32_e32 v211, v211
	v_add_f32_e32 v207, v197, v207
	s_waitcnt lgkmcnt(3)
	v_mfma_f32_32x32x16_bf16 v[80:95], v[240:243], v[120:123], v[80:95]
	v_exp_f32_e32 v212, v212
	v_add_f32_e32 v207, v216, v207
	v_exp_f32_e32 v213, v213
	v_add_f32_e32 v207, v209, v207
	v_exp_f32_e32 v214, v214
	v_add_f32_e32 v207, v210, v207
	v_exp_f32_e32 v215, v215
	s_waitcnt lgkmcnt(2)
	v_mfma_f32_32x32x16_bf16 v[64:79], v[244:247], v[120:123], v[64:79]
	ds_read_b128 v[240:243], v189 offset:32896
	ds_read_b128 v[244:247], v189 offset:41088
	v_add_f32_e32 v207, v211, v207
	v_exp_f32_e32 v217, v208
	v_add_f32_e32 v207, v212, v207
	v_exp_f32_e32 v218, v225
	v_add_f32_e32 v207, v213, v207
	v_exp_f32_e32 v219, v226
	s_waitcnt lgkmcnt(3)
	v_mfma_f32_32x32x16_bf16 v[80:95], v[228:231], v[124:127], v[80:95]
	v_add_f32_e32 v207, v214, v207
	v_add_f32_e32 v207, v215, v207
	v_add_f32_e32 v207, v217, v207
	v_add_f32_e32 v207, v218, v207
	v_add_f32_e32 v207, v219, v207
	v_add_f32_e32 v207, v221, v207
	s_waitcnt lgkmcnt(2)
	v_mfma_f32_32x32x16_bf16 v[64:79], v[232:235], v[124:127], v[64:79]
	ds_read_b128 v[228:231], v199 offset:32896
	ds_read_b128 v[232:235], v199 offset:41088
	s_waitcnt lgkmcnt(3)
	v_mfma_f32_32x32x16_bf16 v[80:95], v[240:243], v[116:119], v[80:95]
	s_waitcnt lgkmcnt(2)
	v_mfma_f32_32x32x16_bf16 v[64:79], v[244:247], v[116:119], v[64:79]
	ds_read_b128 v[240:243], v192 offset:32896
	ds_read_b128 v[244:247], v192 offset:41088
	s_waitcnt lgkmcnt(3)
	v_mfma_f32_32x32x16_bf16 v[80:95], v[228:231], v[104:107], v[80:95]
	s_waitcnt lgkmcnt(2)
	v_mfma_f32_32x32x16_bf16 v[64:79], v[232:235], v[104:107], v[64:79]
	ds_read_b128 v[228:231], v191 offset:32896
	ds_read_b128 v[232:235], v191 offset:41088
	s_waitcnt lgkmcnt(3)
	v_mfma_f32_32x32x16_bf16 v[80:95], v[240:243], v[100:103], v[80:95]
	s_waitcnt lgkmcnt(2)
	v_mfma_f32_32x32x16_bf16 v[64:79], v[244:247], v[100:103], v[64:79]
	v_cvt_pk_bf16_f32 v160, v160, v175
	v_cvt_pk_bf16_f32 v161, v161, v174
	v_cvt_pk_bf16_f32 v162, v162, v173
	v_cvt_pk_bf16_f32 v163, v163, v172
	v_cvt_pk_bf16_f32 v164, v164, v171
	v_cvt_pk_bf16_f32 v165, v165, v170
	s_waitcnt lgkmcnt(1)
	v_mfma_f32_32x32x16_bf16 v[80:95], v[228:231], v[96:99], v[80:95]
	v_cvt_pk_bf16_f32 v166, v166, v169
	v_cvt_pk_bf16_f32 v167, v167, v168
	v_cvt_pk_bf16_f32 v168, v194, v195
	v_cvt_pk_bf16_f32 v169, v196, v197
	v_cvt_pk_bf16_f32 v170, v216, v209
	v_cvt_pk_bf16_f32 v171, v210, v211
	v_cvt_pk_bf16_f32 v172, v212, v213
	s_waitcnt lgkmcnt(0)
	v_mfma_f32_32x32x16_bf16 v[64:79], v[232:235], v[96:99], v[64:79]
	v_cvt_pk_bf16_f32 v173, v214, v215
	v_cvt_pk_bf16_f32 v174, v217, v218
	v_cvt_pk_bf16_f32 v175, v219, v221
	s_add_i32 s50, s50, 2
	s_cmp_ge_u32 s50, s49
	s_cselect_b64 s[44:45], -1, 0
	s_and_b64 vcc, exec, s[44:45]
	s_cbranch_vccnz .Lattn_skip_loads
	global_load_dwordx4 v[128:131], v198, s[52:53]
	global_load_dwordx4 v[132:135], v198, s[52:53] offset:-512
	global_load_dwordx4 v[136:139], v200, s[52:53]
	global_load_dwordx4 v[140:143], v200, s[52:53] offset:-512
	s_add_u32 s52, s52, 0x60000
	s_addc_u32 s53, s53, 0
